# GEMM loop: the 18 s_nop pads between m0 writes and LDS-DMA loads replaced by moving the neighbouring address computation between them
# baseline (speedup 1.0000x reference)
; #define PG8_STAGE(bufoff, gbase, voff) do { _Pragma("unroll") for (int _i = 0; _i < 2; ++_i) \
;         __builtin_amdgcn_global_load_lds((const unsigned*)((const char*)(gbase) + (voff)[_i]), (LAS unsigned*)(lds + (bufoff) + ldsw + _i * 8192), 16, 0, 0); } while (0)
; #define PG8_LDA(dst, b, h) do { _Pragma("unroll") for (int m = 0; m < 4; ++m) _Pragma("unroll") for (int k = 0; k < 2; ++k) dst[m][k] = *(const LAS bf16x8*)(lds + PG8_SA(b, h) + aoff + m * 2048 + k * 1024); } while (0)
; #define PG8_LDB(dst, b, h) do { _Pragma("unroll") for (int n = 0; n < 2; ++n) _Pragma("unroll") for (int k = 0; k < 2; ++k) dst[n][k] = *(const LAS bf16x8*)(lds + PG8_SB(b, h) + boff + n * 2048 + k * 1024); } while (0)
; #define PG8_MMA(ai, bj, At, Bt) do { __builtin_amdgcn_s_setprio(1); _Pragma("unroll") for (int m = 0; m < 4; ++m) _Pragma("unroll") for (int n = 0; n < 2; ++n) _Pragma("unroll") for (int k = 0; k < 2; ++k) \
;         acc[ai][bj][m][n] = __builtin_amdgcn_mfma_f32_16x16x32_bf16(Bt[n][k], At[m][k], acc[ai][bj][m][n], 0, 0, 0); __builtin_amdgcn_s_setprio(0); } while (0)
; #define PG8_WAIT_V(n) asm volatile("s_waitcnt vmcnt(" #n ")" ::: "memory")
; #define PG8_WAIT_L(n) asm volatile("s_waitcnt lgkmcnt(" #n ")" ::: "memory")
; #define PG8_BAR __builtin_amdgcn_s_barrier()
; __device__ __forceinline__ void gemm_phase(LAS unsigned char* lds, const Params& p, const Sched& S, float alpha, const int TIDX) {
;     ...
;         for (int t = 0; t < nt; t += 2) {
;             const bool last = (t == nt - 2);
;             const char* a1 = cA + (size_t)(t + 1) * kstep;
;             const char* a2 = last ? nA : cA + (size_t)(t + 2) * kstep; const char* b2 = last ? nB : cB + (size_t)(t + 2) * kstep;
;             const char* a3 = a2 + kstep; const char* b3 = b2 + kstep;
;             PG8_LDB(B0, 0, 0); PG8_SCHED; PG8_LDA(At, 0, 0); PG8_STAGE(PG8_SA(1, 1), a1 + hstep, voffA);
;             PG8_WAIT_L(8); PG8_BAR; PG8_WAIT_L(0); PG8_MMA(0, 0, At, B0); PG8_BAR; PG8_SCHED;
;             PG8_LDB(B1, 0, 1); PG8_STAGE(PG8_SB(0, 0), b2, voffB);
;             PG8_BAR; PG8_WAIT_L(0); PG8_MMA(0, 1, At, B1); PG8_BAR;
;             PG8_LDA(At, 0, 1); PG8_STAGE(PG8_SA(0, 0), a2, voffA);
;             PG8_BAR; PG8_WAIT_L(0); PG8_MMA(1, 0, At, B0); PG8_BAR; PG8_SCHED;
;             PG8_STAGE(PG8_SB(0, 1), b2 + hstep, voffB);
;             PG8_WAIT_V(6); PG8_BAR; PG8_MMA(1, 1, At, B1); PG8_BAR;
.Lgemm_prio_done:
	s_add_i32 s57, s48, 2
	s_add_u32 s50, s6, 0x80
	s_addc_u32 s49, s7, 0
	s_add_i32 s74, 0, 0x10000
	v_add_u32_e32 v0, s74, v200
	ds_read_b128 v[130:133], v0
	ds_read_b128 v[134:137], v0 offset:1024
	ds_read_b128 v[154:157], v0 offset:2048
	ds_read_b128 v[158:161], v0 offset:3072
	s_cmp_eq_u32 s38, s48
	s_cselect_b32 s48, s44, s50
	s_cselect_b32 s49, s45, s49
	s_cselect_b32 s51, s47, s56
	s_cselect_b32 s50, s46, s39
	v_lshl_add_u64 v[166:167], s[6:7], 0, v[150:151]
	s_add_i32 m0, s35, 0xc000
	ds_read_b128 v[162:165], v202
	ds_read_b128 v[170:173], v202 offset:1024
	ds_read_b128 v[174:177], v202 offset:2048
	ds_read_b128 v[178:181], v202 offset:3072
	ds_read_b128 v[182:185], v202 offset:4096
	ds_read_b128 v[204:207], v202 offset:5120
	ds_read_b128 v[208:211], v202 offset:6144
	ds_read_b128 v[212:215], v202 offset:7168
	global_load_lds_dwordx4 v[166:167], off
	s_add_i32 m0, s35, 0xe000
	v_lshl_add_u64 v[166:167], s[6:7], 0, v[152:153]
	global_load_lds_dwordx4 v[166:167], off
	s_waitcnt lgkmcnt(8)
	s_barrier
	s_waitcnt lgkmcnt(0)
	v_mfma_f32_16x16x32_bf16 v[126:129], v[130:133], v[162:165], 0
	v_mfma_f32_16x16x32_bf16 v[118:121], v[154:157], v[162:165], 0
	v_mfma_f32_16x16x32_bf16 v[110:113], v[130:133], v[174:177], 0
	v_mfma_f32_16x16x32_bf16 v[102:105], v[154:157], v[174:177], 0
	v_mfma_f32_16x16x32_bf16 v[94:97], v[130:133], v[182:185], 0
	v_mfma_f32_16x16x32_bf16 v[86:89], v[154:157], v[182:185], 0
	v_mfma_f32_16x16x32_bf16 v[78:81], v[130:133], v[208:211], 0
	v_mfma_f32_16x16x32_bf16 v[70:73], v[154:157], v[208:211], 0
	v_mfma_f32_16x16x32_bf16 v[126:129], v[134:137], v[170:173], v[126:129]
	v_mfma_f32_16x16x32_bf16 v[118:121], v[158:161], v[170:173], v[118:121]
	v_mfma_f32_16x16x32_bf16 v[110:113], v[134:137], v[178:181], v[110:113]
	v_mfma_f32_16x16x32_bf16 v[102:105], v[158:161], v[178:181], v[102:105]
	v_mfma_f32_16x16x32_bf16 v[94:97], v[134:137], v[204:207], v[94:97]
	v_mfma_f32_16x16x32_bf16 v[86:89], v[158:161], v[204:207], v[86:89]
	v_mfma_f32_16x16x32_bf16 v[78:81], v[134:137], v[212:215], v[78:81]
	v_mfma_f32_16x16x32_bf16 v[70:73], v[158:161], v[212:215], v[70:73]
	s_barrier
	s_add_i32 s75, 0, 0x14000
	s_add_i32 s74, s74, s34
	v_add_u32_e32 v0, s75, v200
	v_lshl_add_u64 v[166:167], s[50:51], 0, v[140:141]
	s_mov_b32 m0, s74
	ds_read_b128 v[216:219], v0
	ds_read_b128 v[220:223], v0 offset:1024
	ds_read_b128 v[224:227], v0 offset:2048
	ds_read_b128 v[228:231], v0 offset:3072
	global_load_lds_dwordx4 v[166:167], off
	s_add_i32 m0, s74, 0x2000
	v_lshl_add_u64 v[186:187], s[50:51], 0, v[144:145]
	global_load_lds_dwordx4 v[186:187], off
	s_barrier
	s_waitcnt lgkmcnt(0)
	v_mfma_f32_16x16x32_bf16 v[122:125], v[216:219], v[162:165], 0
	v_mfma_f32_16x16x32_bf16 v[114:117], v[224:227], v[162:165], 0
	v_mfma_f32_16x16x32_bf16 v[106:109], v[216:219], v[174:177], 0
	v_mfma_f32_16x16x32_bf16 v[98:101], v[224:227], v[174:177], 0
	v_mfma_f32_16x16x32_bf16 v[90:93], v[216:219], v[182:185], 0
	v_mfma_f32_16x16x32_bf16 v[82:85], v[224:227], v[182:185], 0
	v_mfma_f32_16x16x32_bf16 v[74:77], v[216:219], v[208:211], 0
	v_mfma_f32_16x16x32_bf16 v[66:69], v[224:227], v[208:211], 0
	v_mfma_f32_16x16x32_bf16 v[122:125], v[220:223], v[170:173], v[122:125]
	v_mfma_f32_16x16x32_bf16 v[114:117], v[228:231], v[170:173], v[114:117]
	v_mfma_f32_16x16x32_bf16 v[106:109], v[220:223], v[178:181], v[106:109]
	v_mfma_f32_16x16x32_bf16 v[98:101], v[228:231], v[178:181], v[98:101]
	v_mfma_f32_16x16x32_bf16 v[90:93], v[220:223], v[204:207], v[90:93]
	v_mfma_f32_16x16x32_bf16 v[82:85], v[228:231], v[204:207], v[82:85]
	v_mfma_f32_16x16x32_bf16 v[74:77], v[220:223], v[212:215], v[74:77]
	v_mfma_f32_16x16x32_bf16 v[66:69], v[228:231], v[212:215], v[66:69]
	s_mov_b32 m0, s35
	v_lshl_add_u64 v[232:233], s[48:49], 0, v[138:139]
	s_barrier
	ds_read_b128 v[162:165], v202 offset:16384
	ds_read_b128 v[170:173], v202 offset:17408
	ds_read_b128 v[174:177], v202 offset:18432
	ds_read_b128 v[178:181], v202 offset:19456
	ds_read_b128 v[182:185], v202 offset:20480
	ds_read_b128 v[204:207], v202 offset:21504
	ds_read_b128 v[208:211], v202 offset:22528
	ds_read_b128 v[212:215], v202 offset:23552
	global_load_lds_dwordx4 v[232:233], off
	s_mov_b32 m0, s36
	v_lshl_add_u64 v[234:235], s[48:49], 0, v[142:143]
	global_load_lds_dwordx4 v[234:235], off
	s_barrier
	s_waitcnt lgkmcnt(0)
	v_mfma_f32_16x16x32_bf16 v[62:65], v[130:133], v[162:165], 0
	v_mfma_f32_16x16x32_bf16 v[54:57], v[154:157], v[162:165], 0
	v_mfma_f32_16x16x32_bf16 v[46:49], v[130:133], v[174:177], 0
	v_mfma_f32_16x16x32_bf16 v[38:41], v[154:157], v[174:177], 0
	v_mfma_f32_16x16x32_bf16 v[30:33], v[130:133], v[182:185], 0
	v_mfma_f32_16x16x32_bf16 v[22:25], v[154:157], v[182:185], 0
	v_mfma_f32_16x16x32_bf16 v[14:17], v[130:133], v[208:211], 0
	v_mfma_f32_16x16x32_bf16 v[6:9], v[154:157], v[208:211], 0
	v_mfma_f32_16x16x32_bf16 v[62:65], v[134:137], v[170:173], v[62:65]
	v_mfma_f32_16x16x32_bf16 v[54:57], v[158:161], v[170:173], v[54:57]
	v_mfma_f32_16x16x32_bf16 v[46:49], v[134:137], v[178:181], v[46:49]
	v_mfma_f32_16x16x32_bf16 v[38:41], v[158:161], v[178:181], v[38:41]
	v_mfma_f32_16x16x32_bf16 v[30:33], v[134:137], v[204:207], v[30:33]
	v_mfma_f32_16x16x32_bf16 v[22:25], v[158:161], v[204:207], v[22:25]
	v_mfma_f32_16x16x32_bf16 v[14:17], v[134:137], v[212:215], v[14:17]
	v_mfma_f32_16x16x32_bf16 v[6:9], v[158:161], v[212:215], v[6:9]
	s_barrier
	s_add_u32 s50, s50, s20
	s_addc_u32 s51, s51, 0
	s_add_i32 s74, s75, s34
	s_mov_b32 m0, s74
	v_lshl_add_u64 v[236:237], s[50:51], 0, v[140:141]
	global_load_lds_dwordx4 v[236:237], off
	s_add_i32 m0, s74, 0x2000
	v_lshl_add_u64 v[238:239], s[50:51], 0, v[144:145]
	global_load_lds_dwordx4 v[238:239], off
	s_waitcnt vmcnt(6)
	s_barrier
; #define PG8_STAGE(bufoff, gbase, voff) do { _Pragma("unroll") for (int _i = 0; _i < 2; ++_i) \
;         __builtin_amdgcn_global_load_lds((const unsigned*)((const char*)(gbase) + (voff)[_i]), (LAS unsigned*)(lds + (bufoff) + ldsw + _i * 8192), 16, 0, 0); } while (0)
; #define PG8_LDA(dst, b, h) do { _Pragma("unroll") for (int m = 0; m < 4; ++m) _Pragma("unroll") for (int k = 0; k < 2; ++k) dst[m][k] = *(const LAS bf16x8*)(lds + PG8_SA(b, h) + aoff + m * 2048 + k * 1024); } while (0)
; #define PG8_LDB(dst, b, h) do { _Pragma("unroll") for (int n = 0; n < 2; ++n) _Pragma("unroll") for (int k = 0; k < 2; ++k) dst[n][k] = *(const LAS bf16x8*)(lds + PG8_SB(b, h) + boff + n * 2048 + k * 1024); } while (0)
; #define PG8_MMA(ai, bj, At, Bt) do { __builtin_amdgcn_s_setprio(1); _Pragma("unroll") for (int m = 0; m < 4; ++m) _Pragma("unroll") for (int n = 0; n < 2; ++n) _Pragma("unroll") for (int k = 0; k < 2; ++k) \
;         acc[ai][bj][m][n] = __builtin_amdgcn_mfma_f32_16x16x32_bf16(Bt[n][k], At[m][k], acc[ai][bj][m][n], 0, 0, 0); __builtin_amdgcn_s_setprio(0); } while (0)
; #define PG8_WAIT_V(n) asm volatile("s_waitcnt vmcnt(" #n ")" ::: "memory")
; #define PG8_WAIT_L(n) asm volatile("s_waitcnt lgkmcnt(" #n ")" ::: "memory")
; #define PG8_BAR __builtin_amdgcn_s_barrier()
; #define PG8_SCHED __builtin_amdgcn_sched_barrier(0)
; __device__ __forceinline__ void gemm_phase(LAS unsigned char* lds, const Params& p, const Sched& S, float alpha, const int TIDX) {
;     ...
;             PG8_WAIT_V(6); PG8_BAR; PG8_MMA(1, 1, At, B1); PG8_BAR;
;             PG8_LDB(B0, 1, 0); PG8_SCHED; PG8_LDA(At, 1, 0); PG8_STAGE(PG8_SA(0, 1), a2 + hstep, voffA);
;             PG8_WAIT_L(8); PG8_BAR; PG8_WAIT_L(0); PG8_MMA(0, 0, At, B0); PG8_BAR; PG8_SCHED;
;             PG8_LDB(B1, 1, 1); PG8_STAGE(PG8_SB(1, 0), b3, voffB);
;             PG8_BAR; PG8_WAIT_L(0); PG8_MMA(0, 1, At, B1); PG8_BAR;
;             PG8_LDA(At, 1, 1); PG8_STAGE(PG8_SA(1, 0), a3, voffA);
;             PG8_BAR; PG8_WAIT_L(0); PG8_MMA(1, 0, At, B0); PG8_BAR; PG8_SCHED;
	v_mfma_f32_16x16x32_bf16 v[58:61], v[216:219], v[162:165], 0
	v_mfma_f32_16x16x32_bf16 v[50:53], v[224:227], v[162:165], 0
	v_mfma_f32_16x16x32_bf16 v[42:45], v[216:219], v[174:177], 0
	v_mfma_f32_16x16x32_bf16 v[34:37], v[224:227], v[174:177], 0
	v_mfma_f32_16x16x32_bf16 v[26:29], v[216:219], v[182:185], 0
	v_mfma_f32_16x16x32_bf16 v[18:21], v[224:227], v[182:185], 0
	v_mfma_f32_16x16x32_bf16 v[10:13], v[216:219], v[208:211], 0
	v_mfma_f32_16x16x32_bf16 v[2:5], v[224:227], v[208:211], 0
	v_mfma_f32_16x16x32_bf16 v[58:61], v[220:223], v[170:173], v[58:61]
	v_mfma_f32_16x16x32_bf16 v[50:53], v[228:231], v[170:173], v[50:53]
	v_mfma_f32_16x16x32_bf16 v[42:45], v[220:223], v[178:181], v[42:45]
	v_mfma_f32_16x16x32_bf16 v[34:37], v[228:231], v[178:181], v[34:37]
	v_mfma_f32_16x16x32_bf16 v[26:29], v[220:223], v[204:207], v[26:29]
	v_mfma_f32_16x16x32_bf16 v[18:21], v[228:231], v[204:207], v[18:21]
	v_mfma_f32_16x16x32_bf16 v[10:13], v[220:223], v[212:215], v[10:13]
	v_mfma_f32_16x16x32_bf16 v[2:5], v[228:231], v[212:215], v[2:5]
	s_add_i32 s50, 0, 0x18000
	v_add_u32_e32 v0, s50, v200
	s_barrier
	ds_read_b128 v[130:133], v0
	ds_read_b128 v[134:137], v0 offset:1024
	ds_read_b128 v[154:157], v0 offset:2048
	ds_read_b128 v[158:161], v0 offset:3072
	s_add_u32 s48, s48, s20
	s_addc_u32 s49, s49, 0
	s_mov_b32 m0, s37
	v_lshl_add_u64 v[216:217], s[48:49], 0, v[138:139]
	ds_read_b128 v[162:165], v202 offset:32768
	ds_read_b128 v[170:173], v202 offset:33792
	ds_read_b128 v[174:177], v202 offset:34816
	ds_read_b128 v[178:181], v202 offset:35840
	ds_read_b128 v[182:185], v202 offset:36864
	ds_read_b128 v[204:207], v202 offset:37888
	ds_read_b128 v[208:211], v202 offset:38912
	ds_read_b128 v[212:215], v202 offset:39936
	global_load_lds_dwordx4 v[216:217], off
	s_mov_b32 m0, s24
	v_lshl_add_u64 v[216:217], s[48:49], 0, v[142:143]
	global_load_lds_dwordx4 v[216:217], off
	s_waitcnt lgkmcnt(8)
	s_barrier
	s_waitcnt lgkmcnt(0)
	v_mfma_f32_16x16x32_bf16 v[126:129], v[130:133], v[162:165], v[126:129]
	v_mfma_f32_16x16x32_bf16 v[118:121], v[154:157], v[162:165], v[118:121]
	v_mfma_f32_16x16x32_bf16 v[110:113], v[130:133], v[174:177], v[110:113]
	v_mfma_f32_16x16x32_bf16 v[102:105], v[154:157], v[174:177], v[102:105]
	v_mfma_f32_16x16x32_bf16 v[94:97], v[130:133], v[182:185], v[94:97]
	v_mfma_f32_16x16x32_bf16 v[86:89], v[154:157], v[182:185], v[86:89]
	v_mfma_f32_16x16x32_bf16 v[78:81], v[130:133], v[208:211], v[78:81]
	v_mfma_f32_16x16x32_bf16 v[70:73], v[154:157], v[208:211], v[70:73]
	v_mfma_f32_16x16x32_bf16 v[126:129], v[134:137], v[170:173], v[126:129]
	v_mfma_f32_16x16x32_bf16 v[118:121], v[158:161], v[170:173], v[118:121]
	v_mfma_f32_16x16x32_bf16 v[110:113], v[134:137], v[178:181], v[110:113]
	v_mfma_f32_16x16x32_bf16 v[102:105], v[158:161], v[178:181], v[102:105]
	v_mfma_f32_16x16x32_bf16 v[94:97], v[134:137], v[204:207], v[94:97]
	v_mfma_f32_16x16x32_bf16 v[86:89], v[158:161], v[204:207], v[86:89]
	v_mfma_f32_16x16x32_bf16 v[78:81], v[134:137], v[212:215], v[78:81]
	v_mfma_f32_16x16x32_bf16 v[70:73], v[158:161], v[212:215], v[70:73]
	s_barrier
	s_add_i32 s48, 0, 0x1c000
	s_add_i32 s49, s50, s34
	v_add_u32_e32 v0, s48, v200
	v_lshl_add_u64 v[166:167], v[166:167], 0, s[88:89]
	s_mov_b32 m0, s49
	ds_read_b128 v[216:219], v0
	ds_read_b128 v[220:223], v0 offset:1024
	ds_read_b128 v[224:227], v0 offset:2048
	ds_read_b128 v[228:231], v0 offset:3072
	global_load_lds_dwordx4 v[166:167], off
	s_add_i32 m0, s49, 0x2000
	v_lshl_add_u64 v[166:167], v[186:187], 0, s[88:89]
	global_load_lds_dwordx4 v[166:167], off
	s_barrier
	s_waitcnt lgkmcnt(0)
	v_mfma_f32_16x16x32_bf16 v[122:125], v[216:219], v[162:165], v[122:125]
	v_mfma_f32_16x16x32_bf16 v[114:117], v[224:227], v[162:165], v[114:117]
	v_mfma_f32_16x16x32_bf16 v[106:109], v[216:219], v[174:177], v[106:109]
	v_mfma_f32_16x16x32_bf16 v[98:101], v[224:227], v[174:177], v[98:101]
	v_mfma_f32_16x16x32_bf16 v[90:93], v[216:219], v[182:185], v[90:93]
	v_mfma_f32_16x16x32_bf16 v[82:85], v[224:227], v[182:185], v[82:85]
	v_mfma_f32_16x16x32_bf16 v[74:77], v[216:219], v[208:211], v[74:77]
	v_mfma_f32_16x16x32_bf16 v[66:69], v[224:227], v[208:211], v[66:69]
	v_mfma_f32_16x16x32_bf16 v[122:125], v[220:223], v[170:173], v[122:125]
	v_mfma_f32_16x16x32_bf16 v[114:117], v[228:231], v[170:173], v[114:117]
	v_mfma_f32_16x16x32_bf16 v[106:109], v[220:223], v[178:181], v[106:109]
	v_mfma_f32_16x16x32_bf16 v[98:101], v[228:231], v[178:181], v[98:101]
	v_mfma_f32_16x16x32_bf16 v[90:93], v[220:223], v[204:207], v[90:93]
	v_mfma_f32_16x16x32_bf16 v[82:85], v[228:231], v[204:207], v[82:85]
	v_mfma_f32_16x16x32_bf16 v[74:77], v[220:223], v[212:215], v[74:77]
	v_mfma_f32_16x16x32_bf16 v[66:69], v[228:231], v[212:215], v[66:69]
	s_mov_b32 m0, s25
	v_lshl_add_u64 v[166:167], v[232:233], 0, s[88:89]
	s_barrier
	ds_read_b128 v[162:165], v202 offset:49152
	ds_read_b128 v[170:173], v202 offset:50176
	ds_read_b128 v[174:177], v202 offset:51200
	ds_read_b128 v[178:181], v202 offset:52224
	ds_read_b128 v[182:185], v202 offset:53248
	ds_read_b128 v[204:207], v202 offset:54272
	ds_read_b128 v[208:211], v202 offset:55296
	ds_read_b128 v[212:215], v202 offset:56320
	global_load_lds_dwordx4 v[166:167], off
	s_mov_b32 m0, s68
	v_lshl_add_u64 v[166:167], v[234:235], 0, s[88:89]
	global_load_lds_dwordx4 v[166:167], off
	s_barrier
; #define PG8_STAGE(bufoff, gbase, voff) do { _Pragma("unroll") for (int _i = 0; _i < 2; ++_i) \
;         __builtin_amdgcn_global_load_lds((const unsigned*)((const char*)(gbase) + (voff)[_i]), (LAS unsigned*)(lds + (bufoff) + ldsw + _i * 8192), 16, 0, 0); } while (0)
; #define PG8_LDA(dst, b, h) do { _Pragma("unroll") for (int m = 0; m < 4; ++m) _Pragma("unroll") for (int k = 0; k < 2; ++k) dst[m][k] = *(const LAS bf16x8*)(lds + PG8_SA(b, h) + aoff + m * 2048 + k * 1024); } while (0)
; #define PG8_WAIT_V(n) asm volatile("s_waitcnt vmcnt(" #n ")" ::: "memory")
; #define PG8_WAIT_L(n) asm volatile("s_waitcnt lgkmcnt(" #n ")" ::: "memory")
; __device__ __forceinline__ void gemm_phase(LAS unsigned char* lds, const Params& p, const Sched& S, float alpha, const int TIDX) {
;     ...
;         for (int t = 0; t < nt; t += 2) {
;             const bool last = (t == nt - 2);
;             const char* a1 = cA + (size_t)(t + 1) * kstep;
;             const char* a2 = last ? nA : cA + (size_t)(t + 2) * kstep; const char* b2 = last ? nB : cB + (size_t)(t + 2) * kstep;
;             const char* a3 = a2 + kstep; const char* b3 = b2 + kstep;
;             PG8_LDB(B0, 0, 0); PG8_SCHED; PG8_LDA(At, 0, 0); PG8_STAGE(PG8_SA(1, 1), a1 + hstep, voffA);
;             PG8_WAIT_L(8); PG8_BAR; PG8_WAIT_L(0); PG8_MMA(0, 0, At, B0); PG8_BAR; PG8_SCHED;
;             PG8_LDB(B1, 0, 1); PG8_STAGE(PG8_SB(0, 0), b2, voffB);
;             PG8_BAR; PG8_WAIT_L(0); PG8_MMA(0, 1, At, B1); PG8_BAR;
;             PG8_LDA(At, 0, 1); PG8_STAGE(PG8_SA(0, 0), a2, voffA);
;             PG8_BAR; PG8_WAIT_L(0); PG8_MMA(1, 0, At, B0); PG8_BAR; PG8_SCHED;
;             PG8_STAGE(PG8_SB(0, 1), b2 + hstep, voffB);
;             PG8_WAIT_V(6); PG8_BAR; PG8_MMA(1, 1, At, B1); PG8_BAR;
;             PG8_LDB(B0, 1, 0); PG8_SCHED; PG8_LDA(At, 1, 0); PG8_STAGE(PG8_SA(0, 1), a2 + hstep, voffA);
;             PG8_WAIT_L(8); PG8_BAR; PG8_WAIT_L(0); PG8_MMA(0, 0, At, B0); PG8_BAR; PG8_SCHED;
;             PG8_LDB(B1, 1, 1); PG8_STAGE(PG8_SB(1, 0), b3, voffB);
;             PG8_BAR; PG8_WAIT_L(0); PG8_MMA(0, 1, At, B1); PG8_BAR;
;             PG8_LDA(At, 1, 1); PG8_STAGE(PG8_SA(1, 0), a3, voffA);
;             PG8_BAR; PG8_WAIT_L(0); PG8_MMA(1, 0, At, B0); PG8_BAR; PG8_SCHED;
;             PG8_STAGE(PG8_SB(1, 1), b3 + hstep, voffB);
;             PG8_WAIT_V(6); PG8_BAR; PG8_MMA(1, 1, At, B1); PG8_BAR;
	s_waitcnt lgkmcnt(0)
	v_mfma_f32_16x16x32_bf16 v[62:65], v[130:133], v[162:165], v[62:65]
	v_mfma_f32_16x16x32_bf16 v[54:57], v[154:157], v[162:165], v[54:57]
	v_mfma_f32_16x16x32_bf16 v[46:49], v[130:133], v[174:177], v[46:49]
	v_mfma_f32_16x16x32_bf16 v[38:41], v[154:157], v[174:177], v[38:41]
	v_mfma_f32_16x16x32_bf16 v[30:33], v[130:133], v[182:185], v[30:33]
	v_mfma_f32_16x16x32_bf16 v[22:25], v[154:157], v[182:185], v[22:25]
	v_mfma_f32_16x16x32_bf16 v[14:17], v[130:133], v[208:211], v[14:17]
	v_mfma_f32_16x16x32_bf16 v[6:9], v[154:157], v[208:211], v[6:9]
	v_mfma_f32_16x16x32_bf16 v[62:65], v[134:137], v[170:173], v[62:65]
	v_mfma_f32_16x16x32_bf16 v[54:57], v[158:161], v[170:173], v[54:57]
	v_mfma_f32_16x16x32_bf16 v[46:49], v[134:137], v[178:181], v[46:49]
	v_mfma_f32_16x16x32_bf16 v[38:41], v[158:161], v[178:181], v[38:41]
	v_mfma_f32_16x16x32_bf16 v[30:33], v[134:137], v[204:207], v[30:33]
	v_mfma_f32_16x16x32_bf16 v[22:25], v[158:161], v[204:207], v[22:25]
	v_mfma_f32_16x16x32_bf16 v[14:17], v[134:137], v[212:215], v[14:17]
	v_mfma_f32_16x16x32_bf16 v[6:9], v[158:161], v[212:215], v[6:9]
	s_barrier
	s_add_i32 s48, s48, s34
	s_mov_b32 m0, s48
	v_lshl_add_u64 v[130:131], v[236:237], 0, s[88:89]
	global_load_lds_dwordx4 v[130:131], off
	s_add_i32 m0, s48, 0x2000
	v_lshl_add_u64 v[130:131], v[238:239], 0, s[88:89]
	global_load_lds_dwordx4 v[130:131], off
	s_waitcnt vmcnt(6)
	s_barrier
	v_mfma_f32_16x16x32_bf16 v[58:61], v[216:219], v[162:165], v[58:61]
	v_mfma_f32_16x16x32_bf16 v[50:53], v[224:227], v[162:165], v[50:53]
	v_mfma_f32_16x16x32_bf16 v[42:45], v[216:219], v[174:177], v[42:45]
	v_mfma_f32_16x16x32_bf16 v[34:37], v[224:227], v[174:177], v[34:37]
	v_mfma_f32_16x16x32_bf16 v[26:29], v[216:219], v[182:185], v[26:29]
	v_mfma_f32_16x16x32_bf16 v[18:21], v[224:227], v[182:185], v[18:21]
	v_mfma_f32_16x16x32_bf16 v[10:13], v[216:219], v[208:211], v[10:13]
	v_mfma_f32_16x16x32_bf16 v[2:5], v[224:227], v[208:211], v[2:5]
	v_mfma_f32_16x16x32_bf16 v[58:61], v[220:223], v[170:173], v[58:61]
	v_mfma_f32_16x16x32_bf16 v[50:53], v[228:231], v[170:173], v[50:53]
	v_mfma_f32_16x16x32_bf16 v[42:45], v[220:223], v[178:181], v[42:45]
	v_mfma_f32_16x16x32_bf16 v[34:37], v[228:231], v[178:181], v[34:37]
	v_mfma_f32_16x16x32_bf16 v[26:29], v[220:223], v[204:207], v[26:29]
	v_mfma_f32_16x16x32_bf16 v[18:21], v[228:231], v[204:207], v[18:21]
	v_mfma_f32_16x16x32_bf16 v[10:13], v[220:223], v[212:215], v[10:13]
	v_mfma_f32_16x16x32_bf16 v[2:5], v[228:231], v[212:215], v[2:5]
	s_add_u32 s6, s6, 0x100
	s_addc_u32 s7, s7, 0
	s_add_u32 s39, s39, 0x100
	s_addc_u32 s56, s56, 0
	s_cmp_ge_i32 s57, s79
	s_mov_b32 s48, s57
	s_barrier
	s_cbranch_scc0 .LBB0_289
	s_branch .LBB0_291
.LBB0_289:
	s_add_i32 s57, s48, 2
	s_add_u32 s50, s6, 0x80
	s_addc_u32 s49, s7, 0
	s_add_i32 s74, 0, 0x10000
	v_add_u32_e32 v0, s74, v200
	ds_read_b128 v[130:133], v0
	ds_read_b128 v[134:137], v0 offset:1024
	ds_read_b128 v[154:157], v0 offset:2048
	ds_read_b128 v[158:161], v0 offset:3072
	s_cmp_eq_u32 s38, s48
	s_cselect_b32 s48, s44, s50
	s_cselect_b32 s49, s45, s49
	s_cselect_b32 s51, s47, s56
	s_cselect_b32 s50, s46, s39
	v_lshl_add_u64 v[166:167], s[6:7], 0, v[150:151]
	s_add_i32 m0, s35, 0xc000
	ds_read_b128 v[162:165], v202
	ds_read_b128 v[170:173], v202 offset:1024
	ds_read_b128 v[174:177], v202 offset:2048
	ds_read_b128 v[178:181], v202 offset:3072
	ds_read_b128 v[182:185], v202 offset:4096
	ds_read_b128 v[204:207], v202 offset:5120
	ds_read_b128 v[208:211], v202 offset:6144
	ds_read_b128 v[212:215], v202 offset:7168
	global_load_lds_dwordx4 v[166:167], off
	s_add_i32 m0, s35, 0xe000
	v_lshl_add_u64 v[166:167], s[6:7], 0, v[152:153]
	global_load_lds_dwordx4 v[166:167], off
	s_waitcnt lgkmcnt(8)
	s_barrier
	s_waitcnt lgkmcnt(0)
	v_mfma_f32_16x16x32_bf16 v[126:129], v[130:133], v[162:165], v[126:129]
	v_mfma_f32_16x16x32_bf16 v[118:121], v[154:157], v[162:165], v[118:121]
	v_mfma_f32_16x16x32_bf16 v[110:113], v[130:133], v[174:177], v[110:113]
	v_mfma_f32_16x16x32_bf16 v[102:105], v[154:157], v[174:177], v[102:105]
	v_mfma_f32_16x16x32_bf16 v[94:97], v[130:133], v[182:185], v[94:97]
	v_mfma_f32_16x16x32_bf16 v[86:89], v[154:157], v[182:185], v[86:89]
	v_mfma_f32_16x16x32_bf16 v[78:81], v[130:133], v[208:211], v[78:81]
	v_mfma_f32_16x16x32_bf16 v[70:73], v[154:157], v[208:211], v[70:73]
	v_mfma_f32_16x16x32_bf16 v[126:129], v[134:137], v[170:173], v[126:129]
	v_mfma_f32_16x16x32_bf16 v[118:121], v[158:161], v[170:173], v[118:121]
	v_mfma_f32_16x16x32_bf16 v[110:113], v[134:137], v[178:181], v[110:113]
	v_mfma_f32_16x16x32_bf16 v[102:105], v[158:161], v[178:181], v[102:105]
	v_mfma_f32_16x16x32_bf16 v[94:97], v[134:137], v[204:207], v[94:97]
	v_mfma_f32_16x16x32_bf16 v[86:89], v[158:161], v[204:207], v[86:89]
	v_mfma_f32_16x16x32_bf16 v[78:81], v[134:137], v[212:215], v[78:81]
	v_mfma_f32_16x16x32_bf16 v[70:73], v[158:161], v[212:215], v[70:73]
	s_barrier
	s_add_i32 s75, 0, 0x14000
	s_add_i32 s74, s74, s34
	v_add_u32_e32 v0, s75, v200
	v_lshl_add_u64 v[166:167], s[50:51], 0, v[140:141]
	s_mov_b32 m0, s74
	ds_read_b128 v[216:219], v0
	ds_read_b128 v[220:223], v0 offset:1024
	ds_read_b128 v[224:227], v0 offset:2048
	ds_read_b128 v[228:231], v0 offset:3072
	global_load_lds_dwordx4 v[166:167], off
	s_add_i32 m0, s74, 0x2000
	v_lshl_add_u64 v[186:187], s[50:51], 0, v[144:145]
	global_load_lds_dwordx4 v[186:187], off
	s_barrier
; #define PG8_STAGE(bufoff, gbase, voff) do { _Pragma("unroll") for (int _i = 0; _i < 2; ++_i) \
;         __builtin_amdgcn_global_load_lds((const unsigned*)((const char*)(gbase) + (voff)[_i]), (LAS unsigned*)(lds + (bufoff) + ldsw + _i * 8192), 16, 0, 0); } while (0)
; #define PG8_LDA(dst, b, h) do { _Pragma("unroll") for (int m = 0; m < 4; ++m) _Pragma("unroll") for (int k = 0; k < 2; ++k) dst[m][k] = *(const LAS bf16x8*)(lds + PG8_SA(b, h) + aoff + m * 2048 + k * 1024); } while (0)
; #define PG8_LDB(dst, b, h) do { _Pragma("unroll") for (int n = 0; n < 2; ++n) _Pragma("unroll") for (int k = 0; k < 2; ++k) dst[n][k] = *(const LAS bf16x8*)(lds + PG8_SB(b, h) + boff + n * 2048 + k * 1024); } while (0)
; #define PG8_WAIT_V(n) asm volatile("s_waitcnt vmcnt(" #n ")" ::: "memory")
; #define PG8_WAIT_L(n) asm volatile("s_waitcnt lgkmcnt(" #n ")" ::: "memory")
; #define PG8_BAR __builtin_amdgcn_s_barrier()
; #define PG8_SCHED __builtin_amdgcn_sched_barrier(0)
; __device__ __forceinline__ void gemm_phase(LAS unsigned char* lds, const Params& p, const Sched& S, float alpha, const int TIDX) {
;     ...
;             PG8_LDB(B0, 0, 0); PG8_SCHED; PG8_LDA(At, 0, 0); PG8_STAGE(PG8_SA(1, 1), a1 + hstep, voffA);
;             PG8_WAIT_L(8); PG8_BAR; PG8_WAIT_L(0); PG8_MMA(0, 0, At, B0); PG8_BAR; PG8_SCHED;
;             PG8_LDB(B1, 0, 1); PG8_STAGE(PG8_SB(0, 0), b2, voffB);
;             PG8_BAR; PG8_WAIT_L(0); PG8_MMA(0, 1, At, B1); PG8_BAR;
;             PG8_LDA(At, 0, 1); PG8_STAGE(PG8_SA(0, 0), a2, voffA);
;             PG8_BAR; PG8_WAIT_L(0); PG8_MMA(1, 0, At, B0); PG8_BAR; PG8_SCHED;
;             PG8_STAGE(PG8_SB(0, 1), b2 + hstep, voffB);
;             PG8_WAIT_V(6); PG8_BAR; PG8_MMA(1, 1, At, B1); PG8_BAR;
;             PG8_LDB(B0, 1, 0); PG8_SCHED; PG8_LDA(At, 1, 0); PG8_STAGE(PG8_SA(0, 1), a2 + hstep, voffA);
;             PG8_WAIT_L(8); PG8_BAR; PG8_WAIT_L(0); PG8_MMA(0, 0, At, B0); PG8_BAR; PG8_SCHED;
;             PG8_LDB(B1, 1, 1); PG8_STAGE(PG8_SB(1, 0), b3, voffB);
;             PG8_BAR; PG8_WAIT_L(0); PG8_MMA(0, 1, At, B1); PG8_BAR;
;             PG8_LDA(At, 1, 1); PG8_STAGE(PG8_SA(1, 0), a3, voffA);
;             PG8_BAR; PG8_WAIT_L(0); PG8_MMA(1, 0, At, B0); PG8_BAR; PG8_SCHED;
;             PG8_STAGE(PG8_SB(1, 1), b3 + hstep, voffB);
;             PG8_WAIT_V(6); PG8_BAR; PG8_MMA(1, 1, At, B1); PG8_BAR;
	s_waitcnt lgkmcnt(0)
	v_mfma_f32_16x16x32_bf16 v[122:125], v[216:219], v[162:165], v[122:125]
	v_mfma_f32_16x16x32_bf16 v[114:117], v[224:227], v[162:165], v[114:117]
	v_mfma_f32_16x16x32_bf16 v[106:109], v[216:219], v[174:177], v[106:109]
	v_mfma_f32_16x16x32_bf16 v[98:101], v[224:227], v[174:177], v[98:101]
	v_mfma_f32_16x16x32_bf16 v[90:93], v[216:219], v[182:185], v[90:93]
	v_mfma_f32_16x16x32_bf16 v[82:85], v[224:227], v[182:185], v[82:85]
	v_mfma_f32_16x16x32_bf16 v[74:77], v[216:219], v[208:211], v[74:77]
	v_mfma_f32_16x16x32_bf16 v[66:69], v[224:227], v[208:211], v[66:69]
	v_mfma_f32_16x16x32_bf16 v[122:125], v[220:223], v[170:173], v[122:125]
	v_mfma_f32_16x16x32_bf16 v[114:117], v[228:231], v[170:173], v[114:117]
	v_mfma_f32_16x16x32_bf16 v[106:109], v[220:223], v[178:181], v[106:109]
	v_mfma_f32_16x16x32_bf16 v[98:101], v[228:231], v[178:181], v[98:101]
	v_mfma_f32_16x16x32_bf16 v[90:93], v[220:223], v[204:207], v[90:93]
	v_mfma_f32_16x16x32_bf16 v[82:85], v[228:231], v[204:207], v[82:85]
	v_mfma_f32_16x16x32_bf16 v[74:77], v[220:223], v[212:215], v[74:77]
	v_mfma_f32_16x16x32_bf16 v[66:69], v[228:231], v[212:215], v[66:69]
	s_mov_b32 m0, s35
	v_lshl_add_u64 v[232:233], s[48:49], 0, v[138:139]
	s_barrier
	ds_read_b128 v[162:165], v202 offset:16384
	ds_read_b128 v[170:173], v202 offset:17408
	ds_read_b128 v[174:177], v202 offset:18432
	ds_read_b128 v[178:181], v202 offset:19456
	ds_read_b128 v[182:185], v202 offset:20480
	ds_read_b128 v[204:207], v202 offset:21504
	ds_read_b128 v[208:211], v202 offset:22528
	ds_read_b128 v[212:215], v202 offset:23552
	global_load_lds_dwordx4 v[232:233], off
	s_mov_b32 m0, s36
	v_lshl_add_u64 v[234:235], s[48:49], 0, v[142:143]
	global_load_lds_dwordx4 v[234:235], off
	s_barrier
	s_waitcnt lgkmcnt(0)
	v_mfma_f32_16x16x32_bf16 v[62:65], v[130:133], v[162:165], v[62:65]
	v_mfma_f32_16x16x32_bf16 v[54:57], v[154:157], v[162:165], v[54:57]
	v_mfma_f32_16x16x32_bf16 v[46:49], v[130:133], v[174:177], v[46:49]
	v_mfma_f32_16x16x32_bf16 v[38:41], v[154:157], v[174:177], v[38:41]
	v_mfma_f32_16x16x32_bf16 v[30:33], v[130:133], v[182:185], v[30:33]
	v_mfma_f32_16x16x32_bf16 v[22:25], v[154:157], v[182:185], v[22:25]
	v_mfma_f32_16x16x32_bf16 v[14:17], v[130:133], v[208:211], v[14:17]
	v_mfma_f32_16x16x32_bf16 v[6:9], v[154:157], v[208:211], v[6:9]
	v_mfma_f32_16x16x32_bf16 v[62:65], v[134:137], v[170:173], v[62:65]
	v_mfma_f32_16x16x32_bf16 v[54:57], v[158:161], v[170:173], v[54:57]
	v_mfma_f32_16x16x32_bf16 v[46:49], v[134:137], v[178:181], v[46:49]
	v_mfma_f32_16x16x32_bf16 v[38:41], v[158:161], v[178:181], v[38:41]
	v_mfma_f32_16x16x32_bf16 v[30:33], v[134:137], v[204:207], v[30:33]
	v_mfma_f32_16x16x32_bf16 v[22:25], v[158:161], v[204:207], v[22:25]
	v_mfma_f32_16x16x32_bf16 v[14:17], v[134:137], v[212:215], v[14:17]
	v_mfma_f32_16x16x32_bf16 v[6:9], v[158:161], v[212:215], v[6:9]
	s_barrier
	s_add_u32 s50, s50, s20
	s_addc_u32 s51, s51, 0
	s_add_i32 s74, s75, s34
	s_mov_b32 m0, s74
	v_lshl_add_u64 v[236:237], s[50:51], 0, v[140:141]
	global_load_lds_dwordx4 v[236:237], off
	s_add_i32 m0, s74, 0x2000
	v_lshl_add_u64 v[238:239], s[50:51], 0, v[144:145]
	global_load_lds_dwordx4 v[238:239], off
	s_waitcnt vmcnt(6)
	s_barrier
	v_mfma_f32_16x16x32_bf16 v[58:61], v[216:219], v[162:165], v[58:61]
	v_mfma_f32_16x16x32_bf16 v[50:53], v[224:227], v[162:165], v[50:53]
	v_mfma_f32_16x16x32_bf16 v[42:45], v[216:219], v[174:177], v[42:45]
	v_mfma_f32_16x16x32_bf16 v[34:37], v[224:227], v[174:177], v[34:37]
	v_mfma_f32_16x16x32_bf16 v[26:29], v[216:219], v[182:185], v[26:29]
	v_mfma_f32_16x16x32_bf16 v[18:21], v[224:227], v[182:185], v[18:21]
	v_mfma_f32_16x16x32_bf16 v[10:13], v[216:219], v[208:211], v[10:13]
	v_mfma_f32_16x16x32_bf16 v[2:5], v[224:227], v[208:211], v[2:5]
	v_mfma_f32_16x16x32_bf16 v[58:61], v[220:223], v[170:173], v[58:61]
	v_mfma_f32_16x16x32_bf16 v[50:53], v[228:231], v[170:173], v[50:53]
	v_mfma_f32_16x16x32_bf16 v[42:45], v[220:223], v[178:181], v[42:45]
	v_mfma_f32_16x16x32_bf16 v[34:37], v[228:231], v[178:181], v[34:37]
	v_mfma_f32_16x16x32_bf16 v[26:29], v[220:223], v[204:207], v[26:29]
	v_mfma_f32_16x16x32_bf16 v[18:21], v[228:231], v[204:207], v[18:21]
	v_mfma_f32_16x16x32_bf16 v[10:13], v[220:223], v[212:215], v[10:13]
	v_mfma_f32_16x16x32_bf16 v[2:5], v[228:231], v[212:215], v[2:5]
	s_add_i32 s50, 0, 0x18000
	v_add_u32_e32 v0, s50, v200
	s_barrier
	ds_read_b128 v[130:133], v0
	ds_read_b128 v[134:137], v0 offset:1024
	ds_read_b128 v[154:157], v0 offset:2048
	ds_read_b128 v[158:161], v0 offset:3072
	s_add_u32 s48, s48, s20
	s_addc_u32 s49, s49, 0
	s_mov_b32 m0, s37
	v_lshl_add_u64 v[216:217], s[48:49], 0, v[138:139]
	ds_read_b128 v[162:165], v202 offset:32768
	ds_read_b128 v[170:173], v202 offset:33792
	ds_read_b128 v[174:177], v202 offset:34816
	ds_read_b128 v[178:181], v202 offset:35840
	ds_read_b128 v[182:185], v202 offset:36864
	ds_read_b128 v[204:207], v202 offset:37888
	ds_read_b128 v[208:211], v202 offset:38912
	ds_read_b128 v[212:215], v202 offset:39936
	global_load_lds_dwordx4 v[216:217], off
	s_mov_b32 m0, s24
	v_lshl_add_u64 v[216:217], s[48:49], 0, v[142:143]
	global_load_lds_dwordx4 v[216:217], off
	s_waitcnt lgkmcnt(8)
	s_barrier
; #define PG8_STAGE(bufoff, gbase, voff) do { _Pragma("unroll") for (int _i = 0; _i < 2; ++_i) \
;         __builtin_amdgcn_global_load_lds((const unsigned*)((const char*)(gbase) + (voff)[_i]), (LAS unsigned*)(lds + (bufoff) + ldsw + _i * 8192), 16, 0, 0); } while (0)
; #define PG8_LDA(dst, b, h) do { _Pragma("unroll") for (int m = 0; m < 4; ++m) _Pragma("unroll") for (int k = 0; k < 2; ++k) dst[m][k] = *(const LAS bf16x8*)(lds + PG8_SA(b, h) + aoff + m * 2048 + k * 1024); } while (0)
; #define PG8_LDB(dst, b, h) do { _Pragma("unroll") for (int n = 0; n < 2; ++n) _Pragma("unroll") for (int k = 0; k < 2; ++k) dst[n][k] = *(const LAS bf16x8*)(lds + PG8_SB(b, h) + boff + n * 2048 + k * 1024); } while (0)
; #define PG8_WAIT_V(n) asm volatile("s_waitcnt vmcnt(" #n ")" ::: "memory")
; #define PG8_WAIT_L(n) asm volatile("s_waitcnt lgkmcnt(" #n ")" ::: "memory")
; #define PG8_BAR __builtin_amdgcn_s_barrier()
; #define PG8_SCHED __builtin_amdgcn_sched_barrier(0)
; __device__ __forceinline__ void gemm_phase(LAS unsigned char* lds, const Params& p, const Sched& S, float alpha, const int TIDX) {
;     ...
;             PG8_LDB(B0, 0, 0); PG8_SCHED; PG8_LDA(At, 0, 0); PG8_STAGE(PG8_SA(1, 1), a1 + hstep, voffA);
;             PG8_WAIT_L(8); PG8_BAR; PG8_WAIT_L(0); PG8_MMA(0, 0, At, B0); PG8_BAR; PG8_SCHED;
;             PG8_LDB(B1, 0, 1); PG8_STAGE(PG8_SB(0, 0), b2, voffB);
;             PG8_BAR; PG8_WAIT_L(0); PG8_MMA(0, 1, At, B1); PG8_BAR;
;             PG8_LDA(At, 0, 1); PG8_STAGE(PG8_SA(0, 0), a2, voffA);
;             PG8_BAR; PG8_WAIT_L(0); PG8_MMA(1, 0, At, B0); PG8_BAR; PG8_SCHED;
;             PG8_STAGE(PG8_SB(0, 1), b2 + hstep, voffB);
;             PG8_WAIT_V(6); PG8_BAR; PG8_MMA(1, 1, At, B1); PG8_BAR;
;             PG8_LDB(B0, 1, 0); PG8_SCHED; PG8_LDA(At, 1, 0); PG8_STAGE(PG8_SA(0, 1), a2 + hstep, voffA);
;             PG8_WAIT_L(8); PG8_BAR; PG8_WAIT_L(0); PG8_MMA(0, 0, At, B0); PG8_BAR; PG8_SCHED;
;             PG8_LDB(B1, 1, 1); PG8_STAGE(PG8_SB(1, 0), b3, voffB);
;             PG8_BAR; PG8_WAIT_L(0); PG8_MMA(0, 1, At, B1); PG8_BAR;
;             PG8_LDA(At, 1, 1); PG8_STAGE(PG8_SA(1, 0), a3, voffA);
;             PG8_BAR; PG8_WAIT_L(0); PG8_MMA(1, 0, At, B0); PG8_BAR; PG8_SCHED;
;             PG8_STAGE(PG8_SB(1, 1), b3 + hstep, voffB);
;             PG8_WAIT_V(6); PG8_BAR; PG8_MMA(1, 1, At, B1); PG8_BAR;
;         }
	s_waitcnt lgkmcnt(0)
	v_mfma_f32_16x16x32_bf16 v[126:129], v[130:133], v[162:165], v[126:129]
	v_mfma_f32_16x16x32_bf16 v[118:121], v[154:157], v[162:165], v[118:121]
	v_mfma_f32_16x16x32_bf16 v[110:113], v[130:133], v[174:177], v[110:113]
	v_mfma_f32_16x16x32_bf16 v[102:105], v[154:157], v[174:177], v[102:105]
	v_mfma_f32_16x16x32_bf16 v[94:97], v[130:133], v[182:185], v[94:97]
	v_mfma_f32_16x16x32_bf16 v[86:89], v[154:157], v[182:185], v[86:89]
	v_mfma_f32_16x16x32_bf16 v[78:81], v[130:133], v[208:211], v[78:81]
	v_mfma_f32_16x16x32_bf16 v[70:73], v[154:157], v[208:211], v[70:73]
	v_mfma_f32_16x16x32_bf16 v[126:129], v[134:137], v[170:173], v[126:129]
	v_mfma_f32_16x16x32_bf16 v[118:121], v[158:161], v[170:173], v[118:121]
	v_mfma_f32_16x16x32_bf16 v[110:113], v[134:137], v[178:181], v[110:113]
	v_mfma_f32_16x16x32_bf16 v[102:105], v[158:161], v[178:181], v[102:105]
	v_mfma_f32_16x16x32_bf16 v[94:97], v[134:137], v[204:207], v[94:97]
	v_mfma_f32_16x16x32_bf16 v[86:89], v[158:161], v[204:207], v[86:89]
	v_mfma_f32_16x16x32_bf16 v[78:81], v[134:137], v[212:215], v[78:81]
	v_mfma_f32_16x16x32_bf16 v[70:73], v[158:161], v[212:215], v[70:73]
	s_barrier
	s_add_i32 s48, 0, 0x1c000
	s_add_i32 s49, s50, s34
	v_add_u32_e32 v0, s48, v200
	v_lshl_add_u64 v[166:167], v[166:167], 0, s[88:89]
	s_mov_b32 m0, s49
	ds_read_b128 v[216:219], v0
	ds_read_b128 v[220:223], v0 offset:1024
	ds_read_b128 v[224:227], v0 offset:2048
	ds_read_b128 v[228:231], v0 offset:3072
	global_load_lds_dwordx4 v[166:167], off
	s_add_i32 m0, s49, 0x2000
	v_lshl_add_u64 v[166:167], v[186:187], 0, s[88:89]
	global_load_lds_dwordx4 v[166:167], off
	s_barrier
	s_waitcnt lgkmcnt(0)
	v_mfma_f32_16x16x32_bf16 v[122:125], v[216:219], v[162:165], v[122:125]
	v_mfma_f32_16x16x32_bf16 v[114:117], v[224:227], v[162:165], v[114:117]
	v_mfma_f32_16x16x32_bf16 v[106:109], v[216:219], v[174:177], v[106:109]
	v_mfma_f32_16x16x32_bf16 v[98:101], v[224:227], v[174:177], v[98:101]
	v_mfma_f32_16x16x32_bf16 v[90:93], v[216:219], v[182:185], v[90:93]
	v_mfma_f32_16x16x32_bf16 v[82:85], v[224:227], v[182:185], v[82:85]
	v_mfma_f32_16x16x32_bf16 v[74:77], v[216:219], v[208:211], v[74:77]
	v_mfma_f32_16x16x32_bf16 v[66:69], v[224:227], v[208:211], v[66:69]
	v_mfma_f32_16x16x32_bf16 v[122:125], v[220:223], v[170:173], v[122:125]
	v_mfma_f32_16x16x32_bf16 v[114:117], v[228:231], v[170:173], v[114:117]
	v_mfma_f32_16x16x32_bf16 v[106:109], v[220:223], v[178:181], v[106:109]
	v_mfma_f32_16x16x32_bf16 v[98:101], v[228:231], v[178:181], v[98:101]
	v_mfma_f32_16x16x32_bf16 v[90:93], v[220:223], v[204:207], v[90:93]
	v_mfma_f32_16x16x32_bf16 v[82:85], v[228:231], v[204:207], v[82:85]
	v_mfma_f32_16x16x32_bf16 v[74:77], v[220:223], v[212:215], v[74:77]
	v_mfma_f32_16x16x32_bf16 v[66:69], v[228:231], v[212:215], v[66:69]
	s_mov_b32 m0, s25
	v_lshl_add_u64 v[166:167], v[232:233], 0, s[88:89]
	s_barrier
	ds_read_b128 v[162:165], v202 offset:49152
	ds_read_b128 v[170:173], v202 offset:50176
	ds_read_b128 v[174:177], v202 offset:51200
	ds_read_b128 v[178:181], v202 offset:52224
	ds_read_b128 v[182:185], v202 offset:53248
	ds_read_b128 v[204:207], v202 offset:54272
	ds_read_b128 v[208:211], v202 offset:55296
	ds_read_b128 v[212:215], v202 offset:56320
	global_load_lds_dwordx4 v[166:167], off
	s_mov_b32 m0, s68
	v_lshl_add_u64 v[166:167], v[234:235], 0, s[88:89]
	global_load_lds_dwordx4 v[166:167], off
	s_barrier
	s_waitcnt lgkmcnt(0)
	v_mfma_f32_16x16x32_bf16 v[62:65], v[130:133], v[162:165], v[62:65]
	v_mfma_f32_16x16x32_bf16 v[54:57], v[154:157], v[162:165], v[54:57]
	v_mfma_f32_16x16x32_bf16 v[46:49], v[130:133], v[174:177], v[46:49]
	v_mfma_f32_16x16x32_bf16 v[38:41], v[154:157], v[174:177], v[38:41]
	v_mfma_f32_16x16x32_bf16 v[30:33], v[130:133], v[182:185], v[30:33]
	v_mfma_f32_16x16x32_bf16 v[22:25], v[154:157], v[182:185], v[22:25]
	v_mfma_f32_16x16x32_bf16 v[14:17], v[130:133], v[208:211], v[14:17]
	v_mfma_f32_16x16x32_bf16 v[6:9], v[154:157], v[208:211], v[6:9]
	v_mfma_f32_16x16x32_bf16 v[62:65], v[134:137], v[170:173], v[62:65]
	v_mfma_f32_16x16x32_bf16 v[54:57], v[158:161], v[170:173], v[54:57]
	v_mfma_f32_16x16x32_bf16 v[46:49], v[134:137], v[178:181], v[46:49]
	v_mfma_f32_16x16x32_bf16 v[38:41], v[158:161], v[178:181], v[38:41]
	v_mfma_f32_16x16x32_bf16 v[30:33], v[134:137], v[204:207], v[30:33]
	v_mfma_f32_16x16x32_bf16 v[22:25], v[158:161], v[204:207], v[22:25]
	v_mfma_f32_16x16x32_bf16 v[14:17], v[134:137], v[212:215], v[14:17]
	v_mfma_f32_16x16x32_bf16 v[6:9], v[158:161], v[212:215], v[6:9]
	s_barrier
	s_add_i32 s48, s48, s34
	s_mov_b32 m0, s48
	v_lshl_add_u64 v[130:131], v[236:237], 0, s[88:89]
	global_load_lds_dwordx4 v[130:131], off
	s_add_i32 m0, s48, 0x2000
	v_lshl_add_u64 v[130:131], v[238:239], 0, s[88:89]
	global_load_lds_dwordx4 v[130:131], off
	s_waitcnt vmcnt(6)
	s_barrier
	v_mfma_f32_16x16x32_bf16 v[58:61], v[216:219], v[162:165], v[58:61]
	v_mfma_f32_16x16x32_bf16 v[50:53], v[224:227], v[162:165], v[50:53]
	v_mfma_f32_16x16x32_bf16 v[42:45], v[216:219], v[174:177], v[42:45]
	v_mfma_f32_16x16x32_bf16 v[34:37], v[224:227], v[174:177], v[34:37]
	v_mfma_f32_16x16x32_bf16 v[26:29], v[216:219], v[182:185], v[26:29]
	v_mfma_f32_16x16x32_bf16 v[18:21], v[224:227], v[182:185], v[18:21]
	v_mfma_f32_16x16x32_bf16 v[10:13], v[216:219], v[208:211], v[10:13]
	v_mfma_f32_16x16x32_bf16 v[2:5], v[224:227], v[208:211], v[2:5]
	v_mfma_f32_16x16x32_bf16 v[58:61], v[220:223], v[170:173], v[58:61]
	v_mfma_f32_16x16x32_bf16 v[50:53], v[228:231], v[170:173], v[50:53]
	v_mfma_f32_16x16x32_bf16 v[42:45], v[220:223], v[178:181], v[42:45]
	v_mfma_f32_16x16x32_bf16 v[34:37], v[228:231], v[178:181], v[34:37]
	v_mfma_f32_16x16x32_bf16 v[26:29], v[220:223], v[204:207], v[26:29]
	v_mfma_f32_16x16x32_bf16 v[18:21], v[228:231], v[204:207], v[18:21]
	v_mfma_f32_16x16x32_bf16 v[10:13], v[220:223], v[212:215], v[10:13]
	v_mfma_f32_16x16x32_bf16 v[2:5], v[228:231], v[212:215], v[2:5]
	s_add_u32 s6, s6, 0x100
	s_addc_u32 s7, s7, 0
	s_add_u32 s39, s39, 0x100
	s_addc_u32 s56, s56, 0
	s_cmp_ge_i32 s57, s79
	s_mov_b32 s48, s57
	s_barrier
	s_cbranch_scc0 .LBB0_289
	s_branch .LBB0_291
